# gate/up GEMM: SwiGLU epilogue no longer barrier-aligned between wave halves (epilogue of one half overlaps the other half's last MMA / first load phase)
# speedup vs baseline: 1.0095x; 1.0015x over previous
; __device__ __forceinline__ unsigned cvt_pk_bf16(float lo, float hi) { unsigned r; asm volatile("v_cvt_pk_bf16_f32 %0, %1, %2" : "=v"(r) : "v"(lo), "v"(hi)); return r; }
; #define PG8_BAR __builtin_amdgcn_s_barrier()
; __device__ __forceinline__ float silu_mul(float g, float u) { const float e = __builtin_amdgcn_exp2f(-g * 1.4426950408889634f); return g * __builtin_amdgcn_rcpf(1.0f + e) * u; }
;     __device__ __forceinline__ void operator()(const f32x4 (&acc)[2][2][4][2], const Unit& u, int wr, int wc, int fr, int fq) const {
;         asm volatile("" : "+v"(fr), "+v"(fq));
;         const int row0 = u.pm * BM + wr * 64 + fr; const int col0 = u.pn * HALF + wc * 32 + 8 * fq;
; #pragma unroll
;         for (int ai = 0; ai < 2; ++ai)
; #pragma unroll
;             for (int m = 0; m < 4; ++m) { bf16_t* rowp = O + (size_t)(row0 + ai * HALF + m * 16) * ldc + col0;
;                 const f32x4 g0 = acc[ai][0][m][0], g1 = acc[ai][0][m][1], u0 = acc[ai][1][m][0], u1 = acc[ai][1][m][1];
;                 u32x4 w; w.x = cvt_pk_bf16(silu_mul(g0[0], u0[0]), silu_mul(g0[1], u0[1])); w.y = cvt_pk_bf16(silu_mul(g0[2], u0[2]), silu_mul(g0[3], u0[3]));
;                 w.z = cvt_pk_bf16(silu_mul(g1[0], u1[0]), silu_mul(g1[1], u1[1])); w.w = cvt_pk_bf16(silu_mul(g1[2], u1[2]), silu_mul(g1[3], u1[3]));
;                 *(u32x4*)rowp = w; }
;     }
; template <class Epi, bool ALIGN_EPI, bool SP2>
; __device__ __forceinline__ void gemm_phase(LAS unsigned char* lds, const Gemm g, const Sched& S, const Epi& E) {
;     ...
;         if constexpr (ALIGN_EPI) { if (wr == 0) PG8_BAR; }
;         E(acc, cur, wr, wc, fr, fq);
.LBB0_48:
.LBB0_49:
	v_mul_f32_e32 v154, 0xbfb8aa3b, v130
	v_exp_f32_e32 v154, v154
	v_mov_b32_e32 v144, v101
	v_mov_b32_e32 v145, v148
	v_add_f32_e32 v154, 1.0, v154
	v_rcp_f32_e32 v154, v154
	s_lshl_b32 s2, s18, 8
	s_add_i32 s2, s2, s61
	v_add_u32_e32 v151, s2, v144
	v_mul_f32_e32 v130, v130, v154
	v_mul_f32_e32 v126, v126, v130
	v_mul_f32_e32 v130, 0xbfb8aa3b, v131
	v_exp_f32_e32 v130, v130
	s_lshl_b32 s2, s16, 7
	s_or_b32 s2, s2, s62
	v_lshl_add_u32 v146, v145, 3, s2
	v_add_f32_e32 v130, 1.0, v130
	v_rcp_f32_e32 v130, v130
	v_readlane_b32 s2, v253, 10
	v_readlane_b32 s3, v253, 11
	v_ashrrev_i32_e32 v147, 31, v146
	v_mul_f32_e32 v130, v131, v130
	v_mul_f32_e32 v127, v127, v130
	v_cvt_pk_bf16_f32 v126, v126, v127
	v_mul_f32_e32 v127, 0xbfb8aa3b, v132
	v_exp_f32_e32 v127, v127
	v_mov_b64_e32 v[144:145], s[2:3]
	v_mad_i64_i32 v[152:153], s[16:17], v151, s28, v[144:145]
	v_add_f32_e32 v127, 1.0, v127
	v_rcp_f32_e32 v127, v127
	v_lshlrev_b64 v[146:147], 1, v[146:147]
	v_lshl_add_u64 v[152:153], v[152:153], 0, v[146:147]
	s_and_b64 vcc, exec, s[40:41]
	v_mul_f32_e32 v127, v132, v127
	v_mul_f32_e32 v127, v128, v127
	v_mul_f32_e32 v128, 0xbfb8aa3b, v133
	v_exp_f32_e32 v128, v128
	s_nop 0
	v_add_f32_e32 v128, 1.0, v128
	v_rcp_f32_e32 v128, v128
	s_nop 0
	v_mul_f32_e32 v128, v133, v128
	v_mul_f32_e32 v128, v129, v128
	v_cvt_pk_bf16_f32 v127, v127, v128
	v_mul_f32_e32 v128, 0xbfb8aa3b, v122
	v_exp_f32_e32 v128, v128
	s_nop 0
	v_add_f32_e32 v128, 1.0, v128
	v_rcp_f32_e32 v128, v128
	s_nop 0
	v_mul_f32_e32 v122, v122, v128
	v_mul_f32_e32 v118, v118, v122
	v_mul_f32_e32 v122, 0xbfb8aa3b, v123
	v_exp_f32_e32 v122, v122
	s_nop 0
	v_add_f32_e32 v122, 1.0, v122
	v_rcp_f32_e32 v122, v122
	s_nop 0
	v_mul_f32_e32 v122, v123, v122
	v_mul_f32_e32 v119, v119, v122
	v_cvt_pk_bf16_f32 v128, v118, v119
	v_mul_f32_e32 v118, 0xbfb8aa3b, v124
	v_exp_f32_e32 v118, v118
	v_mul_f32_e32 v119, 0xbfb8aa3b, v125
	v_exp_f32_e32 v119, v119
	v_add_f32_e32 v118, 1.0, v118
	v_rcp_f32_e32 v118, v118
	v_add_f32_e32 v119, 1.0, v119
	v_rcp_f32_e32 v119, v119
	v_mul_f32_e32 v118, v124, v118
	v_mul_f32_e32 v118, v120, v118
	v_mul_f32_e32 v120, 0xbfb8aa3b, v114
	v_exp_f32_e32 v120, v120
	v_mul_f32_e32 v119, v125, v119
	v_mul_f32_e32 v119, v121, v119
	v_cvt_pk_bf16_f32 v129, v118, v119
	v_add_f32_e32 v120, 1.0, v120
	v_rcp_f32_e32 v120, v120
	global_store_dwordx4 v[152:153], v[126:129], off
	v_add_u32_e32 v118, 16, v151
	v_mad_i64_i32 v[118:119], s[16:17], v118, s28, v[144:145]
	v_mul_f32_e32 v114, v114, v120
	v_mul_f32_e32 v110, v110, v114
	v_mul_f32_e32 v114, 0xbfb8aa3b, v115
	v_exp_f32_e32 v114, v114
	v_lshl_add_u64 v[118:119], v[118:119], 0, v[146:147]
	v_add_f32_e32 v114, 1.0, v114
	v_rcp_f32_e32 v114, v114
	s_nop 0
	v_mul_f32_e32 v114, v115, v114
	v_mul_f32_e32 v111, v111, v114
	v_cvt_pk_bf16_f32 v110, v110, v111
	v_mul_f32_e32 v111, 0xbfb8aa3b, v116
	v_exp_f32_e32 v111, v111
	s_nop 0
	v_add_f32_e32 v111, 1.0, v111
	v_rcp_f32_e32 v111, v111
	s_nop 0
	v_mul_f32_e32 v111, v116, v111
	v_mul_f32_e32 v111, v112, v111
	v_mul_f32_e32 v112, 0xbfb8aa3b, v117
	v_exp_f32_e32 v112, v112
	s_nop 0
	v_add_f32_e32 v112, 1.0, v112
	v_rcp_f32_e32 v112, v112
	s_nop 0
	v_mul_f32_e32 v112, v117, v112
	v_mul_f32_e32 v112, v113, v112
	v_cvt_pk_bf16_f32 v111, v111, v112
	v_mul_f32_e32 v112, 0xbfb8aa3b, v106
	v_exp_f32_e32 v112, v112
	s_nop 0
	v_add_f32_e32 v112, 1.0, v112
	v_rcp_f32_e32 v112, v112
	s_nop 0
	v_mul_f32_e32 v106, v106, v112
	v_mul_f32_e32 v102, v102, v106
	v_mul_f32_e32 v106, 0xbfb8aa3b, v107
	v_exp_f32_e32 v106, v106
	s_nop 0
	v_add_f32_e32 v106, 1.0, v106
	v_rcp_f32_e32 v106, v106
	s_nop 0
	v_mul_f32_e32 v106, v107, v106
	v_mul_f32_e32 v103, v103, v106
	v_cvt_pk_bf16_f32 v112, v102, v103
	v_mul_f32_e32 v102, 0xbfb8aa3b, v108
	v_exp_f32_e32 v102, v102
	v_mul_f32_e32 v103, 0xbfb8aa3b, v109
	v_exp_f32_e32 v103, v103
	v_add_f32_e32 v102, 1.0, v102
	v_rcp_f32_e32 v102, v102
	v_add_f32_e32 v103, 1.0, v103
	v_rcp_f32_e32 v103, v103
	v_mul_f32_e32 v102, v108, v102
	v_mul_f32_e32 v102, v104, v102
	v_mul_f32_e32 v104, 0xbfb8aa3b, v92
	v_exp_f32_e32 v104, v104
	v_mul_f32_e32 v103, v109, v103
	v_mul_f32_e32 v103, v105, v103
	v_cvt_pk_bf16_f32 v113, v102, v103
	v_add_f32_e32 v104, 1.0, v104
	v_rcp_f32_e32 v104, v104
	global_store_dwordx4 v[118:119], v[110:113], off
	v_add_u32_e32 v102, 32, v151
	v_mad_i64_i32 v[102:103], s[16:17], v102, s28, v[144:145]
	v_mul_f32_e32 v92, v92, v104
	v_mul_f32_e32 v88, v88, v92
	v_mul_f32_e32 v92, 0xbfb8aa3b, v93
	v_exp_f32_e32 v92, v92
	v_lshl_add_u64 v[102:103], v[102:103], 0, v[146:147]
	v_add_f32_e32 v92, 1.0, v92
	v_rcp_f32_e32 v92, v92
	s_nop 0
	v_mul_f32_e32 v92, v93, v92
	v_mul_f32_e32 v89, v89, v92
	v_cvt_pk_bf16_f32 v88, v88, v89
	v_mul_f32_e32 v89, 0xbfb8aa3b, v94
	v_exp_f32_e32 v89, v89
	s_nop 0
	v_add_f32_e32 v89, 1.0, v89
	v_rcp_f32_e32 v89, v89
	s_nop 0
	v_mul_f32_e32 v89, v94, v89
	v_mul_f32_e32 v89, v90, v89
	v_mul_f32_e32 v90, 0xbfb8aa3b, v95
	v_exp_f32_e32 v90, v90
	s_nop 0
	v_add_f32_e32 v90, 1.0, v90
	v_rcp_f32_e32 v90, v90
	s_nop 0
	v_mul_f32_e32 v90, v95, v90
	v_mul_f32_e32 v90, v91, v90
	v_cvt_pk_bf16_f32 v89, v89, v90
	v_mul_f32_e32 v90, 0xbfb8aa3b, v84
	v_exp_f32_e32 v90, v90
	s_nop 0
	v_add_f32_e32 v90, 1.0, v90
	v_rcp_f32_e32 v90, v90
	s_nop 0
	v_mul_f32_e32 v84, v84, v90
	v_mul_f32_e32 v80, v80, v84
	v_mul_f32_e32 v84, 0xbfb8aa3b, v85
	v_exp_f32_e32 v84, v84
	s_nop 0
	v_add_f32_e32 v84, 1.0, v84
	v_rcp_f32_e32 v84, v84
	s_nop 0
	v_mul_f32_e32 v84, v85, v84
	v_mul_f32_e32 v81, v81, v84
	v_cvt_pk_bf16_f32 v90, v80, v81
	v_mul_f32_e32 v80, 0xbfb8aa3b, v86
	v_exp_f32_e32 v80, v80
	v_mul_f32_e32 v81, 0xbfb8aa3b, v87
	v_exp_f32_e32 v81, v81
; __device__ __forceinline__ unsigned cvt_pk_bf16(float lo, float hi) { unsigned r; asm volatile("v_cvt_pk_bf16_f32 %0, %1, %2" : "=v"(r) : "v"(lo), "v"(hi)); return r; }
; __device__ __forceinline__ float silu_mul(float g, float u) { const float e = __builtin_amdgcn_exp2f(-g * 1.4426950408889634f); return g * __builtin_amdgcn_rcpf(1.0f + e) * u; }
;     __device__ __forceinline__ void operator()(const f32x4 (&acc)[2][2][4][2], const Unit& u, int wr, int wc, int fr, int fq) const {
;         asm volatile("" : "+v"(fr), "+v"(fq));
;         const int row0 = u.pm * BM + wr * 64 + fr; const int col0 = u.pn * HALF + wc * 32 + 8 * fq;
; #pragma unroll
;         for (int ai = 0; ai < 2; ++ai)
; #pragma unroll
;             for (int m = 0; m < 4; ++m) { bf16_t* rowp = O + (size_t)(row0 + ai * HALF + m * 16) * ldc + col0;
;                 const f32x4 g0 = acc[ai][0][m][0], g1 = acc[ai][0][m][1], u0 = acc[ai][1][m][0], u1 = acc[ai][1][m][1];
;                 u32x4 w; w.x = cvt_pk_bf16(silu_mul(g0[0], u0[0]), silu_mul(g0[1], u0[1])); w.y = cvt_pk_bf16(silu_mul(g0[2], u0[2]), silu_mul(g0[3], u0[3]));
;                 w.z = cvt_pk_bf16(silu_mul(g1[0], u1[0]), silu_mul(g1[1], u1[1])); w.w = cvt_pk_bf16(silu_mul(g1[2], u1[2]), silu_mul(g1[3], u1[3]));
;                 *(u32x4*)rowp = w; }
;     }
	v_add_f32_e32 v80, 1.0, v80
	v_rcp_f32_e32 v80, v80
	v_add_f32_e32 v81, 1.0, v81
	v_rcp_f32_e32 v81, v81
	v_mul_f32_e32 v80, v86, v80
	v_mul_f32_e32 v80, v82, v80
	v_mul_f32_e32 v82, 0xbfb8aa3b, v76
	v_exp_f32_e32 v82, v82
	v_mul_f32_e32 v81, v87, v81
	v_mul_f32_e32 v81, v83, v81
	v_cvt_pk_bf16_f32 v91, v80, v81
	v_add_f32_e32 v82, 1.0, v82
	v_rcp_f32_e32 v82, v82
	global_store_dwordx4 v[102:103], v[88:91], off
	v_add_u32_e32 v80, 48, v151
	v_mad_i64_i32 v[80:81], s[16:17], v80, s28, v[144:145]
	v_mul_f32_e32 v76, v76, v82
	v_mul_f32_e32 v72, v72, v76
	v_mul_f32_e32 v76, 0xbfb8aa3b, v77
	v_exp_f32_e32 v76, v76
	v_lshl_add_u64 v[80:81], v[80:81], 0, v[146:147]
	v_add_f32_e32 v76, 1.0, v76
	v_rcp_f32_e32 v76, v76
	s_nop 0
	v_mul_f32_e32 v76, v77, v76
	v_mul_f32_e32 v73, v73, v76
	v_cvt_pk_bf16_f32 v72, v72, v73
	v_mul_f32_e32 v73, 0xbfb8aa3b, v78
	v_exp_f32_e32 v73, v73
	s_nop 0
	v_add_f32_e32 v73, 1.0, v73
	v_rcp_f32_e32 v73, v73
	s_nop 0
	v_mul_f32_e32 v73, v78, v73
	v_mul_f32_e32 v73, v74, v73
	v_mul_f32_e32 v74, 0xbfb8aa3b, v79
	v_exp_f32_e32 v74, v74
	s_nop 0
	v_add_f32_e32 v74, 1.0, v74
	v_rcp_f32_e32 v74, v74
	s_nop 0
	v_mul_f32_e32 v74, v79, v74
	v_mul_f32_e32 v74, v75, v74
	v_cvt_pk_bf16_f32 v73, v73, v74
	v_mul_f32_e32 v74, 0xbfb8aa3b, v68
	v_exp_f32_e32 v74, v74
	s_nop 0
	v_add_f32_e32 v74, 1.0, v74
	v_rcp_f32_e32 v74, v74
	s_nop 0
	v_mul_f32_e32 v68, v68, v74
	v_mul_f32_e32 v64, v64, v68
	v_mul_f32_e32 v68, 0xbfb8aa3b, v69
	v_exp_f32_e32 v68, v68
	s_nop 0
	v_add_f32_e32 v68, 1.0, v68
	v_rcp_f32_e32 v68, v68
	s_nop 0
	v_mul_f32_e32 v68, v69, v68
	v_mul_f32_e32 v65, v65, v68
	v_cvt_pk_bf16_f32 v74, v64, v65
	v_mul_f32_e32 v64, 0xbfb8aa3b, v70
	v_exp_f32_e32 v64, v64
	v_mul_f32_e32 v65, 0xbfb8aa3b, v71
	v_exp_f32_e32 v65, v65
	v_add_f32_e32 v64, 1.0, v64
	v_rcp_f32_e32 v64, v64
	v_add_f32_e32 v65, 1.0, v65
	v_rcp_f32_e32 v65, v65
	v_mul_f32_e32 v64, v70, v64
	v_mul_f32_e32 v64, v66, v64
	v_mul_f32_e32 v66, 0xbfb8aa3b, v60
	v_exp_f32_e32 v66, v66
	v_mul_f32_e32 v65, v71, v65
	v_mul_f32_e32 v65, v67, v65
	v_cvt_pk_bf16_f32 v75, v64, v65
	v_add_f32_e32 v66, 1.0, v66
	v_rcp_f32_e32 v66, v66
	global_store_dwordx4 v[80:81], v[72:75], off
	v_add_u32_e32 v64, 0x80, v151
	v_mad_i64_i32 v[64:65], s[16:17], v64, s28, v[144:145]
	v_mul_f32_e32 v60, v60, v66
	v_mul_f32_e32 v56, v56, v60
	v_mul_f32_e32 v60, 0xbfb8aa3b, v61
	v_exp_f32_e32 v60, v60
	v_lshl_add_u64 v[64:65], v[64:65], 0, v[146:147]
	v_add_f32_e32 v60, 1.0, v60
	v_rcp_f32_e32 v60, v60
	s_nop 0
	v_mul_f32_e32 v60, v61, v60
	v_mul_f32_e32 v57, v57, v60
	v_cvt_pk_bf16_f32 v56, v56, v57
	v_mul_f32_e32 v57, 0xbfb8aa3b, v62
	v_exp_f32_e32 v57, v57
	s_nop 0
	v_add_f32_e32 v57, 1.0, v57
	v_rcp_f32_e32 v57, v57
	s_nop 0
	v_mul_f32_e32 v57, v62, v57
	v_mul_f32_e32 v57, v58, v57
	v_mul_f32_e32 v58, 0xbfb8aa3b, v63
	v_exp_f32_e32 v58, v58
	s_nop 0
	v_add_f32_e32 v58, 1.0, v58
	v_rcp_f32_e32 v58, v58
	s_nop 0
	v_mul_f32_e32 v58, v63, v58
	v_mul_f32_e32 v58, v59, v58
	v_cvt_pk_bf16_f32 v57, v57, v58
	v_mul_f32_e32 v58, 0xbfb8aa3b, v52
	v_exp_f32_e32 v58, v58
	s_nop 0
	v_add_f32_e32 v58, 1.0, v58
	v_rcp_f32_e32 v58, v58
	s_nop 0
	v_mul_f32_e32 v52, v52, v58
	v_mul_f32_e32 v48, v48, v52
	v_mul_f32_e32 v52, 0xbfb8aa3b, v53
	v_exp_f32_e32 v52, v52
	s_nop 0
	v_add_f32_e32 v52, 1.0, v52
	v_rcp_f32_e32 v52, v52
	s_nop 0
	v_mul_f32_e32 v52, v53, v52
	v_mul_f32_e32 v49, v49, v52
	v_cvt_pk_bf16_f32 v58, v48, v49
	v_mul_f32_e32 v48, 0xbfb8aa3b, v54
	v_exp_f32_e32 v48, v48
	v_mul_f32_e32 v49, 0xbfb8aa3b, v55
	v_exp_f32_e32 v49, v49
	v_add_f32_e32 v48, 1.0, v48
	v_rcp_f32_e32 v48, v48
	v_add_f32_e32 v49, 1.0, v49
	v_rcp_f32_e32 v49, v49
	v_mul_f32_e32 v48, v54, v48
	v_mul_f32_e32 v48, v50, v48
	v_mul_f32_e32 v50, 0xbfb8aa3b, v44
	v_exp_f32_e32 v50, v50
	v_mul_f32_e32 v49, v55, v49
	v_mul_f32_e32 v49, v51, v49
	v_cvt_pk_bf16_f32 v59, v48, v49
	v_add_f32_e32 v50, 1.0, v50
	v_rcp_f32_e32 v50, v50
	global_store_dwordx4 v[64:65], v[56:59], off
	v_add_u32_e32 v48, 0x90, v151
	v_mad_i64_i32 v[48:49], s[16:17], v48, s28, v[144:145]
	v_mul_f32_e32 v44, v44, v50
	v_mul_f32_e32 v40, v40, v44
	v_mul_f32_e32 v44, 0xbfb8aa3b, v45
	v_exp_f32_e32 v44, v44
	v_lshl_add_u64 v[48:49], v[48:49], 0, v[146:147]
	v_add_f32_e32 v44, 1.0, v44
	v_rcp_f32_e32 v44, v44
	s_nop 0
	v_mul_f32_e32 v44, v45, v44
	v_mul_f32_e32 v41, v41, v44
	v_cvt_pk_bf16_f32 v40, v40, v41
	v_mul_f32_e32 v41, 0xbfb8aa3b, v46
	v_exp_f32_e32 v41, v41
	s_nop 0
	v_add_f32_e32 v41, 1.0, v41
	v_rcp_f32_e32 v41, v41
	s_nop 0
	v_mul_f32_e32 v41, v46, v41
	v_mul_f32_e32 v41, v42, v41
	v_mul_f32_e32 v42, 0xbfb8aa3b, v47
; __device__ __forceinline__ unsigned cvt_pk_bf16(float lo, float hi) { unsigned r; asm volatile("v_cvt_pk_bf16_f32 %0, %1, %2" : "=v"(r) : "v"(lo), "v"(hi)); return r; }
; #define PG8_BAR __builtin_amdgcn_s_barrier()
; __device__ __forceinline__ float silu_mul(float g, float u) { const float e = __builtin_amdgcn_exp2f(-g * 1.4426950408889634f); return g * __builtin_amdgcn_rcpf(1.0f + e) * u; }
;     __device__ __forceinline__ void operator()(const f32x4 (&acc)[2][2][4][2], const Unit& u, int wr, int wc, int fr, int fq) const {
;         asm volatile("" : "+v"(fr), "+v"(fq));
;         const int row0 = u.pm * BM + wr * 64 + fr; const int col0 = u.pn * HALF + wc * 32 + 8 * fq;
; #pragma unroll
;         for (int ai = 0; ai < 2; ++ai)
; #pragma unroll
;             for (int m = 0; m < 4; ++m) { bf16_t* rowp = O + (size_t)(row0 + ai * HALF + m * 16) * ldc + col0;
;                 const f32x4 g0 = acc[ai][0][m][0], g1 = acc[ai][0][m][1], u0 = acc[ai][1][m][0], u1 = acc[ai][1][m][1];
;                 u32x4 w; w.x = cvt_pk_bf16(silu_mul(g0[0], u0[0]), silu_mul(g0[1], u0[1])); w.y = cvt_pk_bf16(silu_mul(g0[2], u0[2]), silu_mul(g0[3], u0[3]));
;                 w.z = cvt_pk_bf16(silu_mul(g1[0], u1[0]), silu_mul(g1[1], u1[1])); w.w = cvt_pk_bf16(silu_mul(g1[2], u1[2]), silu_mul(g1[3], u1[3]));
;                 *(u32x4*)rowp = w; }
;     }
; template <class Epi, bool ALIGN_EPI, bool SP2>
; __device__ __forceinline__ void gemm_phase(LAS unsigned char* lds, const Gemm g, const Sched& S, const Epi& E) {
;     ...
;         if (!has_next) break;
; #pragma unroll
;         for (int a = 0; a < 2; ++a)
; #pragma unroll
;             for (int b = 0; b < 2; ++b)
; #pragma unroll
;                 for (int m = 0; m < 4; ++m)
; #pragma unroll
;                     for (int n = 0; n < 2; ++n) acc[a][b][m][n] = (f32x4){0.f, 0.f, 0.f, 0.f};
;         cur = nxt; cA = nA; cB = nB; ++ui;
;         if constexpr (ALIGN_EPI) { if (wr == 1) PG8_BAR; }
	v_exp_f32_e32 v42, v42
	s_nop 0
	v_add_f32_e32 v42, 1.0, v42
	v_rcp_f32_e32 v42, v42
	s_nop 0
	v_mul_f32_e32 v42, v47, v42
	v_mul_f32_e32 v42, v43, v42
	v_cvt_pk_bf16_f32 v41, v41, v42
	v_mul_f32_e32 v42, 0xbfb8aa3b, v36
	v_exp_f32_e32 v42, v42
	s_nop 0
	v_add_f32_e32 v42, 1.0, v42
	v_rcp_f32_e32 v42, v42
	s_nop 0
	v_mul_f32_e32 v36, v36, v42
	v_mul_f32_e32 v32, v32, v36
	v_mul_f32_e32 v36, 0xbfb8aa3b, v37
	v_exp_f32_e32 v36, v36
	s_nop 0
	v_add_f32_e32 v36, 1.0, v36
	v_rcp_f32_e32 v36, v36
	s_nop 0
	v_mul_f32_e32 v36, v37, v36
	v_mul_f32_e32 v33, v33, v36
	v_cvt_pk_bf16_f32 v42, v32, v33
	v_mul_f32_e32 v32, 0xbfb8aa3b, v38
	v_exp_f32_e32 v32, v32
	v_mul_f32_e32 v33, 0xbfb8aa3b, v39
	v_exp_f32_e32 v33, v33
	v_add_f32_e32 v32, 1.0, v32
	v_rcp_f32_e32 v32, v32
	v_add_f32_e32 v33, 1.0, v33
	v_rcp_f32_e32 v33, v33
	v_mul_f32_e32 v32, v38, v32
	v_mul_f32_e32 v32, v34, v32
	v_mul_f32_e32 v34, 0xbfb8aa3b, v28
	v_exp_f32_e32 v34, v34
	v_mul_f32_e32 v33, v39, v33
	v_mul_f32_e32 v33, v35, v33
	v_cvt_pk_bf16_f32 v43, v32, v33
	v_add_f32_e32 v34, 1.0, v34
	v_rcp_f32_e32 v34, v34
	global_store_dwordx4 v[48:49], v[40:43], off
	v_add_u32_e32 v32, 0xa0, v151
	v_mad_i64_i32 v[32:33], s[16:17], v32, s28, v[144:145]
	v_mul_f32_e32 v28, v28, v34
	v_mul_f32_e32 v24, v24, v28
	v_mul_f32_e32 v28, 0xbfb8aa3b, v29
	v_exp_f32_e32 v28, v28
	v_lshl_add_u64 v[32:33], v[32:33], 0, v[146:147]
	v_add_f32_e32 v28, 1.0, v28
	v_rcp_f32_e32 v28, v28
	s_nop 0
	v_mul_f32_e32 v28, v29, v28
	v_mul_f32_e32 v25, v25, v28
	v_cvt_pk_bf16_f32 v24, v24, v25
	v_mul_f32_e32 v25, 0xbfb8aa3b, v30
	v_exp_f32_e32 v25, v25
	s_nop 0
	v_add_f32_e32 v25, 1.0, v25
	v_rcp_f32_e32 v25, v25
	s_nop 0
	v_mul_f32_e32 v25, v30, v25
	v_mul_f32_e32 v25, v26, v25
	v_mul_f32_e32 v26, 0xbfb8aa3b, v31
	v_exp_f32_e32 v26, v26
	s_nop 0
	v_add_f32_e32 v26, 1.0, v26
	v_rcp_f32_e32 v26, v26
	s_nop 0
	v_mul_f32_e32 v26, v31, v26
	v_mul_f32_e32 v26, v27, v26
	v_cvt_pk_bf16_f32 v25, v25, v26
	v_mul_f32_e32 v26, 0xbfb8aa3b, v20
	v_exp_f32_e32 v26, v26
	s_nop 0
	v_add_f32_e32 v26, 1.0, v26
	v_rcp_f32_e32 v26, v26
	s_nop 0
	v_mul_f32_e32 v20, v20, v26
	v_mul_f32_e32 v16, v16, v20
	v_mul_f32_e32 v20, 0xbfb8aa3b, v21
	v_exp_f32_e32 v20, v20
	s_nop 0
	v_add_f32_e32 v20, 1.0, v20
	v_rcp_f32_e32 v20, v20
	s_nop 0
	v_mul_f32_e32 v20, v21, v20
	v_mul_f32_e32 v17, v17, v20
	v_cvt_pk_bf16_f32 v26, v16, v17
	v_mul_f32_e32 v16, 0xbfb8aa3b, v22
	v_exp_f32_e32 v16, v16
	v_mul_f32_e32 v17, 0xbfb8aa3b, v23
	v_exp_f32_e32 v17, v17
	v_add_f32_e32 v16, 1.0, v16
	v_rcp_f32_e32 v16, v16
	v_add_f32_e32 v17, 1.0, v17
	v_rcp_f32_e32 v17, v17
	v_mul_f32_e32 v16, v22, v16
	v_mul_f32_e32 v16, v18, v16
	v_mul_f32_e32 v18, 0xbfb8aa3b, v12
	v_exp_f32_e32 v18, v18
	v_mul_f32_e32 v17, v23, v17
	v_mul_f32_e32 v17, v19, v17
	v_cvt_pk_bf16_f32 v27, v16, v17
	v_add_f32_e32 v18, 1.0, v18
	v_rcp_f32_e32 v18, v18
	global_store_dwordx4 v[32:33], v[24:27], off
	v_add_u32_e32 v16, 0xb0, v151
	v_mad_i64_i32 v[16:17], s[16:17], v16, s28, v[144:145]
	v_mul_f32_e32 v12, v12, v18
	v_mul_f32_e32 v8, v8, v12
	v_mul_f32_e32 v12, 0xbfb8aa3b, v13
	v_exp_f32_e32 v12, v12
	v_lshl_add_u64 v[16:17], v[16:17], 0, v[146:147]
	s_mov_b64 s[16:17], -1
	v_add_f32_e32 v12, 1.0, v12
	v_rcp_f32_e32 v12, v12
	s_nop 0
	v_mul_f32_e32 v12, v13, v12
	v_mul_f32_e32 v9, v9, v12
	v_cvt_pk_bf16_f32 v8, v8, v9
	v_mul_f32_e32 v9, 0xbfb8aa3b, v14
	v_exp_f32_e32 v9, v9
	s_nop 0
	v_add_f32_e32 v9, 1.0, v9
	v_rcp_f32_e32 v9, v9
	s_nop 0
	v_mul_f32_e32 v9, v14, v9
	v_mul_f32_e32 v9, v10, v9
	v_mul_f32_e32 v10, 0xbfb8aa3b, v15
	v_exp_f32_e32 v10, v10
	s_nop 0
	v_add_f32_e32 v10, 1.0, v10
	v_rcp_f32_e32 v10, v10
	s_nop 0
	v_mul_f32_e32 v10, v15, v10
	v_mul_f32_e32 v10, v11, v10
	v_cvt_pk_bf16_f32 v9, v9, v10
	v_mul_f32_e32 v10, 0xbfb8aa3b, v4
	v_exp_f32_e32 v10, v10
	s_nop 0
	v_add_f32_e32 v10, 1.0, v10
	v_rcp_f32_e32 v10, v10
	s_nop 0
	v_mul_f32_e32 v4, v4, v10
	v_mul_f32_e32 v0, v0, v4
	v_mul_f32_e32 v4, 0xbfb8aa3b, v5
	v_exp_f32_e32 v4, v4
	s_nop 0
	v_add_f32_e32 v4, 1.0, v4
	v_rcp_f32_e32 v4, v4
	s_nop 0
	v_mul_f32_e32 v4, v5, v4
	v_mul_f32_e32 v1, v1, v4
	v_cvt_pk_bf16_f32 v10, v0, v1
	v_mul_f32_e32 v0, 0xbfb8aa3b, v6
	v_mul_f32_e32 v1, 0xbfb8aa3b, v7
	v_exp_f32_e32 v0, v0
	v_exp_f32_e32 v1, v1
	v_add_f32_e32 v0, 1.0, v0
	v_add_f32_e32 v1, 1.0, v1
	v_rcp_f32_e32 v0, v0
	v_rcp_f32_e32 v1, v1
	v_mul_f32_e32 v0, v6, v0
	v_mul_f32_e32 v1, v7, v1
	v_mul_f32_e32 v0, v2, v0
	v_mul_f32_e32 v1, v3, v1
	v_cvt_pk_bf16_f32 v11, v0, v1
	global_store_dwordx4 v[16:17], v[8:11], off
	s_cbranch_vccnz .LBB0_34
	s_andn2_b64 vcc, exec, s[8:9]
	s_cbranch_vccnz .LBB0_33
	s_branch .LBB0_33

; #define PG8_WAIT_V(n) asm volatile("s_waitcnt vmcnt(" #n ")" ::: "memory")
; #define PG8_BAR __builtin_amdgcn_s_barrier()
; template <class Epi, bool ALIGN_EPI, bool SP2>
; __device__ __forceinline__ void gemm_phase(LAS unsigned char* lds, const Gemm g, const Sched& S, const Epi& E) {
;     ...
;     PG8_WAIT_V(0);
;     if constexpr (!ALIGN_EPI) { if (wr == 0) PG8_BAR; }
;     PG8_BAR;
; __global__ void __launch_bounds__(512, 2) mk_fwd(Args a) {
;     ...
;                 if (nM == MT / 256) { const int idle = (nM * (2 * FF / 256)) % G;
;                     if (G == 256) { if (ph == 2) side_convert(lds, idle, SIDE_Q, 0, SIDE_E0); else if (ph == 9) side_convert(lds, idle, SIDE_Q, SIDE_E1, SIDE_E2); else if (ph == 12) side_convert(lds, idle, SIDE_Q, SIDE_E2, SIDE_E3 < SIDE_END ? SIDE_E3 : SIDE_END); } }
.LBB0_75:
	s_waitcnt vmcnt(0)
	v_readlane_b32 s68, v254, 46
	v_readlane_b32 s69, v254, 47
	s_movk_i32 s58, 0xb0
	s_movk_i32 s59, 0x41ff
	s_movk_i32 s60, 0x4dff
	s_movk_i32 s61, 0x2bff
	s_mov_b32 s63, 0xafff
	s_mov_b32 s65, 0x107ff
	s_mov_b32 s62, 0x119ff
	s_mov_b32 s64, 0xea00
	s_mov_b32 s66, 0x1600000
	s_mov_b32 s67, 0xf800000
	s_mov_b64 s[34:35], s[84:85]
	v_readlane_b32 s36, v254, 60
	s_and_b64 vcc, exec, s[10:11]
	s_cbranch_vccz .Lge_noextra
	s_barrier
.Lge_noextra:
	s_barrier
.LBB0_76:
	s_xor_b64 s[6:7], s[6:7], -1
	s_andn2_b64 vcc, exec, s[6:7]
	s_cbranch_vccnz .LBB0_287
	v_readlane_b32 s2, v253, 19
	v_readlane_b32 s3, v253, 20
	s_andn2_b64 vcc, exec, s[2:3]
	s_cbranch_vccnz .LBB0_287
	s_cmp_lt_i32 s72, 9
	s_mov_b64 s[6:7], -1
	s_cbranch_scc1 .LBB0_276
	s_cmp_lt_i32 s72, 12
	s_cbranch_scc1 .LBB0_237
	s_cmp_eq_u32 s72, 12
	s_cbranch_scc0 .LBB0_236
	s_mov_b32 s6, s80
	v_readlane_b32 s2, v254, 35
	s_cmp_lt_i32 s6, s2
	s_cbranch_scc1 .LBB0_236
	v_mov_b32_e32 v2, v216
	s_lshl_b32 s2, s6, 6
	v_ashrrev_i32_e32 v0, 6, v2
	v_lshl_add_u32 v4, v0, 14, 0
	v_lshlrev_b32_e32 v5, 3, v0
	v_bfe_u32 v3, v2, 5, 1
	v_and_b32_e32 v0, 31, v2
	v_bfe_u32 v15, v2, 3, 3
	v_lshlrev_b32_e32 v2, 3, v2
	v_lshlrev_b32_e32 v6, 2, v0
	v_mul_u32_u24_e32 v7, 0x84, v3
	v_and_b32_e32 v2, 56, v2
	s_add_i32 s3, s2, 0x2a80
	v_add3_u32 v14, v4, v6, v7
	v_mul_u32_u24_e32 v6, 0x84, v2
	v_lshlrev_b32_e32 v7, 2, v15
	v_add_u32_e32 v1, s3, v5
	v_add3_u32 v16, v4, v6, v7
	v_or_b32_e32 v17, 8, v15
	v_or_b32_e32 v18, 16, v15
	v_or_b32_e32 v19, 24, v15
	v_add_u32_e32 v20, s2, v5
	s_mov_b32 s22, 0
	v_mov_b32_e32 v21, -8
	s_branch .LBB0_196
